# RES epilogue: nt (streaming) policy on the 32 f32 residual x stores; xg stores unchanged
# speedup vs baseline: 1.1964x; 1.0113x over previous
.LBB0_546:
	s_and_b64 s[28:29], s[46:47], exec
	v_readlane_b32 s4, v253, 39
	s_cselect_b32 s29, s43, 0
	s_cselect_b32 s28, s42, s72
	v_readlane_b32 s3, v252, 12
	v_readlane_b32 s18, v253, 53
	v_readlane_b32 s19, v253, 54
	v_readlane_b32 s20, v252, 11
	s_cselect_b32 s3, s19, s3
	s_cselect_b32 s30, s18, s20
	s_lshl_b64 s[28:29], s[28:29], 20
	s_add_u32 s28, s30, s28
	s_addc_u32 s29, s3, s29
	s_and_b64 s[44:45], s[46:47], exec
	v_readlane_b32 s5, v253, 40
	s_cselect_b32 s83, s43, 0
	s_cselect_b32 s82, s42, s42
	s_lshl_b64 s[42:43], s[82:83], 19
	v_readlane_b32 s4, v252, 9
	v_readlane_b32 s5, v252, 10
	s_add_u32 s42, s4, s42
	v_lshlrev_b64 v[234:235], 10, v[232:233]
	s_addc_u32 s43, s5, s43
	v_lshlrev_b64 v[236:237], 11, v[232:233]
	v_lshl_add_u64 v[216:217], s[42:43], 0, v[236:237]
	v_lshl_add_u64 v[234:235], v[234:235], 2, s[28:29]
	v_lshl_add_u64 v[236:237], v[238:239], 2, v[234:235]
	v_lshl_add_u64 v[234:235], v[238:239], 1, v[216:217]
	s_waitcnt vmcnt(0)
	v_pk_fma_f32 v[138:139], v[126:127], v[202:203], v[138:139]
	v_pk_fma_f32 v[136:137], v[124:125], v[200:201], v[136:137]
	v_pk_fma_f32 v[146:147], v[122:123], v[174:175], v[146:147]
	v_pk_fma_f32 v[144:145], v[120:121], v[172:173], v[144:145]
	s_and_b64 vcc, exec, s[40:41]
	v_readlane_b32 s6, v253, 41
	v_readlane_b32 s7, v253, 42
	v_readlane_b32 s8, v253, 43
	v_readlane_b32 s9, v253, 44
	v_readlane_b32 s10, v253, 45
	v_readlane_b32 s11, v253, 46
	v_readlane_b32 s12, v253, 47
	v_readlane_b32 s13, v253, 48
	v_readlane_b32 s14, v253, 49
	v_readlane_b32 s15, v253, 50
	v_readlane_b32 s16, v253, 51
	v_readlane_b32 s17, v253, 52
	global_store_dwordx4 v[236:237], v[136:139], off nt
	global_store_dwordx4 v[236:237], v[144:147], off offset:16 nt
	s_cbranch_vccnz .LBB0_548
	v_pk_mul_f32 v[122:123], v[138:139], v[198:199]
	v_pk_mul_f32 v[120:121], v[136:137], v[196:197]
	v_pk_mul_f32 v[124:125], v[146:147], v[194:195]
	v_pk_mul_f32 v[126:127], v[144:145], v[192:193]
	v_cvt_pk_bf16_f32 v120, v120, v121
	v_cvt_pk_bf16_f32 v121, v122, v123
	s_nop 0
	v_cvt_pk_bf16_f32 v122, v126, v127
	v_cvt_pk_bf16_f32 v123, v124, v125
	global_store_dwordx4 v[234:235], v[120:123], off
.LBB0_548:
	v_pk_fma_f32 v[140:141], v[112:113], v[172:173], v[140:141]
	v_add_co_u32_e32 v112, vcc, 0x10000, v236
	v_pk_fma_f32 v[126:127], v[118:119], v[202:203], v[206:207]
	s_nop 0
	v_addc_co_u32_e32 v113, vcc, 0, v237, vcc
	v_pk_fma_f32 v[124:125], v[116:117], v[200:201], v[204:205]
	v_pk_fma_f32 v[142:143], v[114:115], v[174:175], v[142:143]
	s_and_b64 vcc, exec, s[40:41]
	s_brev_b32 s44, 60
	global_store_dwordx4 v[112:113], v[124:127], off nt
	global_store_dwordx4 v[112:113], v[140:143], off offset:16 nt
	s_cbranch_vccnz .LBB0_550
	v_pk_mul_f32 v[114:115], v[126:127], v[198:199]
	v_pk_mul_f32 v[112:113], v[124:125], v[196:197]
	v_pk_mul_f32 v[116:117], v[142:143], v[194:195]
	v_pk_mul_f32 v[118:119], v[140:141], v[192:193]
	v_cvt_pk_bf16_f32 v112, v112, v113
	v_cvt_pk_bf16_f32 v113, v114, v115
	s_nop 0
	v_cvt_pk_bf16_f32 v114, v118, v119
	v_cvt_pk_bf16_f32 v115, v116, v117
	v_add_co_u32_e32 v116, vcc, 0x8000, v234
	s_nop 1
	v_addc_co_u32_e32 v117, vcc, 0, v235, vcc
	global_store_dwordx4 v[116:117], v[112:115], off
.LBB0_550:
	v_pk_fma_f32 v[164:165], v[104:105], v[172:173], v[164:165]
	v_add_co_u32_e32 v104, vcc, 0x20000, v236
	v_pk_fma_f32 v[162:163], v[110:111], v[202:203], v[162:163]
	s_nop 0
	v_addc_co_u32_e32 v105, vcc, 0, v237, vcc
	v_pk_fma_f32 v[160:161], v[108:109], v[200:201], v[160:161]
	v_pk_fma_f32 v[166:167], v[106:107], v[174:175], v[166:167]
	s_and_b64 vcc, exec, s[40:41]
	s_mov_b32 s4, 0x10000
	s_mov_b32 s5, 0x20000
	global_store_dwordx4 v[104:105], v[160:163], off nt
	global_store_dwordx4 v[104:105], v[164:167], off offset:16 nt
	s_cbranch_vccnz .LBB0_552
	v_pk_mul_f32 v[106:107], v[162:163], v[198:199]
	v_pk_mul_f32 v[104:105], v[160:161], v[196:197]
	v_pk_mul_f32 v[108:109], v[166:167], v[194:195]
	v_pk_mul_f32 v[110:111], v[164:165], v[192:193]
	v_cvt_pk_bf16_f32 v104, v104, v105
	v_cvt_pk_bf16_f32 v105, v106, v107
	s_nop 0
	v_cvt_pk_bf16_f32 v106, v110, v111
	v_cvt_pk_bf16_f32 v107, v108, v109
	v_add_co_u32_e32 v108, vcc, 0x10000, v234
	s_nop 1
	v_addc_co_u32_e32 v109, vcc, 0, v235, vcc
	global_store_dwordx4 v[108:109], v[104:107], off
.LBB0_552:
	v_pk_fma_f32 v[172:173], v[96:97], v[172:173], v[148:149]
	v_add_co_u32_e32 v96, vcc, 0x30000, v236
	v_pk_fma_f32 v[170:171], v[102:103], v[202:203], v[170:171]
	s_nop 0
	v_addc_co_u32_e32 v97, vcc, 0, v237, vcc
	v_pk_fma_f32 v[168:169], v[100:101], v[200:201], v[168:169]
	v_pk_fma_f32 v[174:175], v[98:99], v[174:175], v[150:151]
	s_and_b64 vcc, exec, s[40:41]
	global_store_dwordx4 v[96:97], v[168:171], off nt
	global_store_dwordx4 v[96:97], v[172:175], off offset:16 nt
	s_cbranch_vccnz .LBB0_554
	v_pk_mul_f32 v[98:99], v[170:171], v[198:199]
	v_pk_mul_f32 v[96:97], v[168:169], v[196:197]
	v_pk_mul_f32 v[100:101], v[174:175], v[194:195]
	v_pk_mul_f32 v[102:103], v[172:173], v[192:193]
	v_cvt_pk_bf16_f32 v96, v96, v97
	v_cvt_pk_bf16_f32 v97, v98, v99
	s_nop 0
	v_cvt_pk_bf16_f32 v98, v102, v103
	v_cvt_pk_bf16_f32 v99, v100, v101
	v_add_co_u32_e32 v100, vcc, 0x18000, v234
	s_nop 1
	v_addc_co_u32_e32 v101, vcc, 0, v235, vcc
	global_store_dwordx4 v[100:101], v[96:99], off

.LBB0_556:
	s_waitcnt vmcnt(0)
	v_pk_fma_f32 v[94:95], v[94:95], v[206:207], v[190:191]
	v_pk_fma_f32 v[92:93], v[92:93], v[204:205], v[188:189]
	v_pk_fma_f32 v[90:91], v[90:91], v[202:203], v[186:187]
	v_pk_fma_f32 v[88:89], v[88:89], v[200:201], v[184:185]
	s_and_b64 vcc, exec, s[40:41]
	global_store_dwordx4 v[236:237], v[92:95], off offset:512 nt
	global_store_dwordx4 v[236:237], v[88:91], off offset:528 nt
	s_cbranch_vccnz .LBB0_558
	v_pk_mul_f32 v[186:187], v[94:95], v[198:199]
	v_pk_mul_f32 v[184:185], v[92:93], v[196:197]
	v_pk_mul_f32 v[188:189], v[90:91], v[194:195]
	v_pk_mul_f32 v[190:191], v[88:89], v[192:193]
	v_cvt_pk_bf16_f32 v184, v184, v185
	v_cvt_pk_bf16_f32 v185, v186, v187
	s_nop 0
	v_cvt_pk_bf16_f32 v186, v190, v191
	v_cvt_pk_bf16_f32 v187, v188, v189
	global_store_dwordx4 v[234:235], v[184:187], off offset:256
.LBB0_558:
	v_pk_fma_f32 v[80:81], v[80:81], v[200:201], v[176:177]
	v_add_co_u32_e32 v176, vcc, 0x10000, v236
	v_pk_fma_f32 v[86:87], v[86:87], v[206:207], v[182:183]
	s_nop 0
	v_addc_co_u32_e32 v177, vcc, 0, v237, vcc
	v_pk_fma_f32 v[84:85], v[84:85], v[204:205], v[180:181]
	v_pk_fma_f32 v[82:83], v[82:83], v[202:203], v[178:179]
	s_and_b64 vcc, exec, s[40:41]
	global_store_dwordx4 v[176:177], v[84:87], off offset:512 nt
	global_store_dwordx4 v[176:177], v[80:83], off offset:528 nt
	s_cbranch_vccnz .LBB0_560
	v_pk_mul_f32 v[178:179], v[86:87], v[198:199]
	v_pk_mul_f32 v[176:177], v[84:85], v[196:197]
	v_pk_mul_f32 v[180:181], v[82:83], v[194:195]
	v_pk_mul_f32 v[182:183], v[80:81], v[192:193]
	v_cvt_pk_bf16_f32 v176, v176, v177
	v_cvt_pk_bf16_f32 v177, v178, v179
	s_nop 0
	v_cvt_pk_bf16_f32 v178, v182, v183
	v_cvt_pk_bf16_f32 v179, v180, v181
	v_add_co_u32_e32 v180, vcc, 0x8000, v234
	s_nop 1
	v_addc_co_u32_e32 v181, vcc, 0, v235, vcc
	global_store_dwordx4 v[180:181], v[176:179], off offset:256
.LBB0_560:
	v_pk_fma_f32 v[72:73], v[72:73], v[200:201], v[152:153]
	v_add_co_u32_e32 v152, vcc, 0x20000, v236
	v_pk_fma_f32 v[78:79], v[78:79], v[206:207], v[158:159]
	s_nop 0
	v_addc_co_u32_e32 v153, vcc, 0, v237, vcc
	v_pk_fma_f32 v[76:77], v[76:77], v[204:205], v[156:157]
	v_pk_fma_f32 v[74:75], v[74:75], v[202:203], v[154:155]
	s_and_b64 vcc, exec, s[40:41]
	global_store_dwordx4 v[152:153], v[76:79], off offset:512 nt
	global_store_dwordx4 v[152:153], v[72:75], off offset:528 nt
	s_cbranch_vccnz .LBB0_562
	v_pk_mul_f32 v[154:155], v[78:79], v[198:199]
	v_pk_mul_f32 v[152:153], v[76:77], v[196:197]
	v_pk_mul_f32 v[156:157], v[74:75], v[194:195]
	v_pk_mul_f32 v[158:159], v[72:73], v[192:193]
	v_cvt_pk_bf16_f32 v152, v152, v153
	v_cvt_pk_bf16_f32 v153, v154, v155
	s_nop 0
	v_cvt_pk_bf16_f32 v154, v158, v159
	v_cvt_pk_bf16_f32 v155, v156, v157
	v_add_co_u32_e32 v156, vcc, 0x10000, v234
	s_nop 1
	v_addc_co_u32_e32 v157, vcc, 0, v235, vcc
	global_store_dwordx4 v[156:157], v[152:155], off offset:256
.LBB0_562:
	v_pk_fma_f32 v[64:65], v[64:65], v[200:201], v[128:129]
	v_add_co_u32_e32 v128, vcc, 0x30000, v236
	v_pk_fma_f32 v[70:71], v[70:71], v[206:207], v[134:135]
	s_nop 0
	v_addc_co_u32_e32 v129, vcc, 0, v237, vcc
	v_pk_fma_f32 v[68:69], v[68:69], v[204:205], v[132:133]
	v_pk_fma_f32 v[66:67], v[66:67], v[202:203], v[130:131]
	s_and_b64 vcc, exec, s[40:41]
	global_store_dwordx4 v[128:129], v[68:71], off offset:512 nt
	global_store_dwordx4 v[128:129], v[64:67], off offset:528 nt
	s_cbranch_vccnz .LBB0_564
	v_pk_mul_f32 v[130:131], v[70:71], v[198:199]
	v_pk_mul_f32 v[128:129], v[68:69], v[196:197]
	v_pk_mul_f32 v[132:133], v[66:67], v[194:195]
	v_pk_mul_f32 v[134:135], v[64:65], v[192:193]
	v_cvt_pk_bf16_f32 v128, v128, v129
	v_cvt_pk_bf16_f32 v129, v130, v131
	s_nop 0
	v_cvt_pk_bf16_f32 v130, v134, v135
	v_cvt_pk_bf16_f32 v131, v132, v133
	v_add_co_u32_e32 v132, vcc, 0x18000, v234
	s_nop 1
	v_addc_co_u32_e32 v133, vcc, 0, v235, vcc
	global_store_dwordx4 v[132:133], v[128:131], off offset:256

.LBB0_574:
	s_waitcnt vmcnt(1)
	v_pk_fma_f32 v[56:57], v[56:57], v[132:133], v[120:121]
	v_add_co_u32_e32 v120, vcc, 0x80000, v236
	s_waitcnt vmcnt(0)
	v_pk_fma_f32 v[62:63], v[62:63], v[138:139], v[150:151]
	v_addc_co_u32_e32 v121, vcc, 0, v237, vcc
	v_pk_fma_f32 v[60:61], v[60:61], v[136:137], v[148:149]
	v_pk_fma_f32 v[58:59], v[58:59], v[134:135], v[122:123]
	s_and_b64 vcc, exec, s[40:41]
	global_store_dwordx4 v[120:121], v[60:63], off nt
	global_store_dwordx4 v[120:121], v[56:59], off offset:16 nt
	s_cbranch_vccnz .LBB0_576
	v_pk_mul_f32 v[122:123], v[62:63], v[130:131]
	v_pk_mul_f32 v[120:121], v[60:61], v[128:129]
	v_pk_mul_f32 v[140:141], v[58:59], v[126:127]
	v_pk_mul_f32 v[142:143], v[56:57], v[124:125]
	v_cvt_pk_bf16_f32 v120, v120, v121
	v_cvt_pk_bf16_f32 v121, v122, v123
	s_nop 0
	v_cvt_pk_bf16_f32 v122, v142, v143
	v_cvt_pk_bf16_f32 v123, v140, v141
	v_add_co_u32_e32 v140, vcc, 0x40000, v234
	s_nop 1
	v_addc_co_u32_e32 v141, vcc, 0, v235, vcc
	global_store_dwordx4 v[140:141], v[120:123], off
.LBB0_576:
	v_pk_fma_f32 v[48:49], v[48:49], v[132:133], v[112:113]
	v_add_co_u32_e32 v112, vcc, 0x90000, v236
	v_pk_fma_f32 v[54:55], v[54:55], v[138:139], v[118:119]
	s_nop 0
	v_addc_co_u32_e32 v113, vcc, 0, v237, vcc
	v_pk_fma_f32 v[52:53], v[52:53], v[136:137], v[116:117]
	v_pk_fma_f32 v[50:51], v[50:51], v[134:135], v[114:115]
	s_and_b64 vcc, exec, s[40:41]
	global_store_dwordx4 v[112:113], v[52:55], off nt
	global_store_dwordx4 v[112:113], v[48:51], off offset:16 nt
	s_cbranch_vccnz .LBB0_578
	v_pk_mul_f32 v[114:115], v[54:55], v[130:131]
	v_pk_mul_f32 v[112:113], v[52:53], v[128:129]
	v_pk_mul_f32 v[116:117], v[50:51], v[126:127]
	v_pk_mul_f32 v[118:119], v[48:49], v[124:125]
	v_cvt_pk_bf16_f32 v112, v112, v113
	v_cvt_pk_bf16_f32 v113, v114, v115
	s_nop 0
	v_cvt_pk_bf16_f32 v114, v118, v119
	v_cvt_pk_bf16_f32 v115, v116, v117
	v_add_co_u32_e32 v116, vcc, 0x48000, v234
	s_nop 1
	v_addc_co_u32_e32 v117, vcc, 0, v235, vcc
	global_store_dwordx4 v[116:117], v[112:115], off
.LBB0_578:
	v_pk_fma_f32 v[40:41], v[40:41], v[132:133], v[104:105]
	v_add_co_u32_e32 v104, vcc, 0xa0000, v236
	v_pk_fma_f32 v[46:47], v[46:47], v[138:139], v[110:111]
	s_nop 0
	v_addc_co_u32_e32 v105, vcc, 0, v237, vcc
	v_pk_fma_f32 v[44:45], v[44:45], v[136:137], v[108:109]
	v_pk_fma_f32 v[42:43], v[42:43], v[134:135], v[106:107]
	s_and_b64 vcc, exec, s[40:41]
	global_store_dwordx4 v[104:105], v[44:47], off nt
	global_store_dwordx4 v[104:105], v[40:43], off offset:16 nt
	s_cbranch_vccnz .LBB0_580
	v_pk_mul_f32 v[106:107], v[46:47], v[130:131]
	v_pk_mul_f32 v[104:105], v[44:45], v[128:129]
	v_pk_mul_f32 v[108:109], v[42:43], v[126:127]
	v_pk_mul_f32 v[110:111], v[40:41], v[124:125]
	v_cvt_pk_bf16_f32 v104, v104, v105
	v_cvt_pk_bf16_f32 v105, v106, v107
	s_nop 0
	v_cvt_pk_bf16_f32 v106, v110, v111
	v_cvt_pk_bf16_f32 v107, v108, v109
	v_add_co_u32_e32 v108, vcc, 0x50000, v234
	s_nop 1
	v_addc_co_u32_e32 v109, vcc, 0, v235, vcc
	global_store_dwordx4 v[108:109], v[104:107], off
.LBB0_580:
	v_pk_fma_f32 v[32:33], v[32:33], v[132:133], v[96:97]
	v_add_co_u32_e32 v96, vcc, 0xb0000, v236
	v_pk_fma_f32 v[38:39], v[38:39], v[138:139], v[102:103]
	s_nop 0
	v_addc_co_u32_e32 v97, vcc, 0, v237, vcc
	v_pk_fma_f32 v[36:37], v[36:37], v[136:137], v[100:101]
	v_pk_fma_f32 v[34:35], v[34:35], v[134:135], v[98:99]
	s_and_b64 vcc, exec, s[40:41]
	global_store_dwordx4 v[96:97], v[36:39], off nt
	global_store_dwordx4 v[96:97], v[32:35], off offset:16 nt
	s_cbranch_vccnz .LBB0_582
	v_pk_mul_f32 v[98:99], v[38:39], v[130:131]
	v_pk_mul_f32 v[96:97], v[36:37], v[128:129]
	v_pk_mul_f32 v[100:101], v[34:35], v[126:127]
	v_pk_mul_f32 v[102:103], v[32:33], v[124:125]
	v_cvt_pk_bf16_f32 v96, v96, v97
	v_cvt_pk_bf16_f32 v97, v98, v99
	s_nop 0
	v_cvt_pk_bf16_f32 v98, v102, v103
	v_cvt_pk_bf16_f32 v99, v100, v101
	v_add_co_u32_e32 v100, vcc, 0x58000, v234
	s_nop 1
	v_addc_co_u32_e32 v101, vcc, 0, v235, vcc
	global_store_dwordx4 v[100:101], v[96:99], off

.LBB0_584:
	s_waitcnt vmcnt(1)
	v_pk_fma_f32 v[24:25], v[24:25], v[104:105], v[88:89]
	v_add_co_u32_e32 v88, vcc, 0x80000, v236
	s_waitcnt vmcnt(0)
	v_pk_fma_f32 v[30:31], v[30:31], v[110:111], v[94:95]
	v_addc_co_u32_e32 v89, vcc, 0, v237, vcc
	v_pk_fma_f32 v[28:29], v[28:29], v[108:109], v[92:93]
	v_pk_fma_f32 v[26:27], v[26:27], v[106:107], v[90:91]
	s_and_b64 vcc, exec, s[40:41]
	global_store_dwordx4 v[88:89], v[28:31], off offset:512 nt
	global_store_dwordx4 v[88:89], v[24:27], off offset:528 nt
	s_cbranch_vccnz .LBB0_586
	v_pk_mul_f32 v[90:91], v[30:31], v[98:99]
	v_pk_mul_f32 v[88:89], v[28:29], v[96:97]
	v_pk_mul_f32 v[92:93], v[26:27], v[102:103]
	v_pk_mul_f32 v[94:95], v[24:25], v[100:101]
	v_cvt_pk_bf16_f32 v88, v88, v89
	v_cvt_pk_bf16_f32 v89, v90, v91
	s_nop 0
	v_cvt_pk_bf16_f32 v90, v94, v95
	v_cvt_pk_bf16_f32 v91, v92, v93
	v_add_co_u32_e32 v92, vcc, 0x40000, v234
	s_nop 1
	v_addc_co_u32_e32 v93, vcc, 0, v235, vcc
	global_store_dwordx4 v[92:93], v[88:91], off offset:256
.LBB0_586:
	v_pk_fma_f32 v[16:17], v[16:17], v[104:105], v[80:81]
	v_add_co_u32_e32 v80, vcc, 0x90000, v236
	v_pk_fma_f32 v[22:23], v[22:23], v[110:111], v[86:87]
	s_nop 0
	v_addc_co_u32_e32 v81, vcc, 0, v237, vcc
	v_pk_fma_f32 v[20:21], v[20:21], v[108:109], v[84:85]
	v_pk_fma_f32 v[18:19], v[18:19], v[106:107], v[82:83]
	s_and_b64 vcc, exec, s[40:41]
	global_store_dwordx4 v[80:81], v[20:23], off offset:512 nt
	global_store_dwordx4 v[80:81], v[16:19], off offset:528 nt
	s_cbranch_vccnz .LBB0_588
	v_pk_mul_f32 v[82:83], v[22:23], v[98:99]
	v_pk_mul_f32 v[80:81], v[20:21], v[96:97]
	v_pk_mul_f32 v[84:85], v[18:19], v[102:103]
	v_pk_mul_f32 v[86:87], v[16:17], v[100:101]
	v_cvt_pk_bf16_f32 v80, v80, v81
	v_cvt_pk_bf16_f32 v81, v82, v83
	s_nop 0
	v_cvt_pk_bf16_f32 v82, v86, v87
	v_cvt_pk_bf16_f32 v83, v84, v85
	v_add_co_u32_e32 v84, vcc, 0x48000, v234
	s_nop 1
	v_addc_co_u32_e32 v85, vcc, 0, v235, vcc
	global_store_dwordx4 v[84:85], v[80:83], off offset:256
.LBB0_588:
	v_pk_fma_f32 v[8:9], v[8:9], v[104:105], v[72:73]
	v_add_co_u32_e32 v72, vcc, 0xa0000, v236
	v_pk_fma_f32 v[14:15], v[14:15], v[110:111], v[78:79]
	s_nop 0
	v_addc_co_u32_e32 v73, vcc, 0, v237, vcc
	v_pk_fma_f32 v[12:13], v[12:13], v[108:109], v[76:77]
	v_pk_fma_f32 v[10:11], v[10:11], v[106:107], v[74:75]
	s_and_b64 vcc, exec, s[40:41]
	global_store_dwordx4 v[72:73], v[12:15], off offset:512 nt
	global_store_dwordx4 v[72:73], v[8:11], off offset:528 nt
	s_cbranch_vccnz .LBB0_590
	v_pk_mul_f32 v[74:75], v[14:15], v[98:99]
	v_pk_mul_f32 v[72:73], v[12:13], v[96:97]
	v_pk_mul_f32 v[76:77], v[10:11], v[102:103]
	v_pk_mul_f32 v[78:79], v[8:9], v[100:101]
	v_cvt_pk_bf16_f32 v72, v72, v73
	v_cvt_pk_bf16_f32 v73, v74, v75
	s_nop 0
	v_cvt_pk_bf16_f32 v74, v78, v79
	v_cvt_pk_bf16_f32 v75, v76, v77
	v_add_co_u32_e32 v76, vcc, 0x50000, v234
	s_nop 1
	v_addc_co_u32_e32 v77, vcc, 0, v235, vcc
	global_store_dwordx4 v[76:77], v[72:75], off offset:256
.LBB0_590:
	v_pk_fma_f32 v[0:1], v[0:1], v[104:105], v[64:65]
	v_add_co_u32_e32 v64, vcc, 0xb0000, v236
	v_pk_fma_f32 v[6:7], v[6:7], v[110:111], v[70:71]
	s_nop 0
	v_addc_co_u32_e32 v65, vcc, 0, v237, vcc
	v_pk_fma_f32 v[4:5], v[4:5], v[108:109], v[68:69]
	v_pk_fma_f32 v[2:3], v[2:3], v[106:107], v[66:67]
	s_and_b64 vcc, exec, s[40:41]
	global_store_dwordx4 v[64:65], v[4:7], off offset:512 nt
	global_store_dwordx4 v[64:65], v[0:3], off offset:528 nt
	s_cbranch_vccnz .LBB0_592
	v_pk_mul_f32 v[66:67], v[6:7], v[98:99]
	v_pk_mul_f32 v[64:65], v[4:5], v[96:97]
	v_pk_mul_f32 v[68:69], v[2:3], v[102:103]
	v_pk_mul_f32 v[70:71], v[0:1], v[100:101]
	v_cvt_pk_bf16_f32 v64, v64, v65
	v_cvt_pk_bf16_f32 v65, v66, v67
	s_nop 0
	v_cvt_pk_bf16_f32 v66, v70, v71
	v_cvt_pk_bf16_f32 v67, v68, v69
	v_add_co_u32_e32 v68, vcc, 0x58000, v234
	s_nop 1
	v_addc_co_u32_e32 v69, vcc, 0, v235, vcc
	global_store_dwordx4 v[68:69], v[64:67], off offset:256
